# attention loops: fragment prefetch reads may still be in flight across the tile barrier (counted lgkmcnt)
# speedup vs baseline: 1.0121x; 1.0107x over previous
.LBB0_365:
	s_cmp_lt_u32 s28, 3
	s_cselect_b32 s2, s43, s23
	v_add_u32_e32 v64, s2, v165
	v_ashrrev_i32_e32 v65, 31, v64
	v_lshlrev_b64 v[64:65], 8, v[64:65]
	v_lshl_add_u64 v[64:65], v[150:151], 0, v[64:65]
	global_load_dwordx4 v[118:121], v[64:65], off
	s_add_i32 s2, s27, 0xffffe000
	s_cmp_lg_u32 s27, 0
	s_cselect_b32 s2, s2, 0x4000
	v_add_u32_e32 v154, s2, v164
	ds_read_b128 v[138:141], v159
	ds_read_b128 v[142:145], v159 offset:32
	ds_read_b128 v[166:169], v159 offset:64
	ds_read_b128 v[170:173], v159 offset:96
	ds_read_b64_tr_b16 v[192:193], v154 offset:34816
	ds_read_b64_tr_b16 v[194:195], v154 offset:35328
	ds_read_b64_tr_b16 v[196:197], v154 offset:35840
	ds_read_b64_tr_b16 v[198:199], v154 offset:36352
	s_waitcnt lgkmcnt(8)
	v_mfma_f32_32x32x16_bf16 v[0:15], v[234:237], v[130:133], v[0:15]
	v_xor_b32_e32 v64, 0x80000000, v162
	v_mov_b32_e32 v65, v64
	v_mov_b64_e32 v[66:67], v[64:65]
	v_mov_b64_e32 v[68:69], v[64:65]
	v_mov_b64_e32 v[70:71], v[64:65]
	v_mov_b64_e32 v[72:73], v[64:65]
	v_mov_b64_e32 v[74:75], v[64:65]
	v_mfma_f32_32x32x16_bf16 v[16:31], v[238:241], v[130:133], v[16:31]
	v_mov_b64_e32 v[76:77], v[64:65]
	v_mov_b64_e32 v[78:79], v[64:65]
	v_exp_f32_e32 v36, v36
	v_exp_f32_e32 v37, v37
	v_exp_f32_e32 v130, v48
	v_mfma_f32_32x32x16_bf16 v[0:15], v[242:245], v[134:137], v[0:15]
	v_exp_f32_e32 v48, v32
	v_exp_f32_e32 v131, v49
	v_exp_f32_e32 v49, v33
	v_exp_f32_e32 v132, v50
	v_mfma_f32_32x32x16_bf16 v[16:31], v[246:249], v[134:137], v[16:31]
	v_exp_f32_e32 v50, v34
	v_exp_f32_e32 v133, v51
	v_exp_f32_e32 v51, v35
	v_exp_f32_e32 v34, v42
	s_waitcnt lgkmcnt(7)
	v_mfma_f32_32x32x16_bf16 v[80:95], v[138:141], v[98:101], v[64:79]
	ds_read_b128 v[138:141], v159 offset:4640
	v_exp_f32_e32 v35, v43
	v_exp_f32_e32 v42, v46
	v_exp_f32_e32 v43, v47
	v_exp_f32_e32 v134, v52
	s_waitcnt lgkmcnt(7)
	v_mfma_f32_32x32x16_bf16 v[80:95], v[142:145], v[102:105], v[80:95]
	ds_read_b128 v[142:145], v159 offset:4672
	v_exp_f32_e32 v135, v53
	v_exp_f32_e32 v136, v54
	v_exp_f32_e32 v137, v55
	v_exp_f32_e32 v54, v58
	s_waitcnt lgkmcnt(7)
	v_mfma_f32_32x32x16_bf16 v[80:95], v[166:169], v[106:109], v[80:95]
	ds_read_b128 v[166:169], v159 offset:4704
	v_exp_f32_e32 v55, v59
	v_exp_f32_e32 v52, v38
	v_exp_f32_e32 v53, v39
	v_exp_f32_e32 v38, v56
	s_waitcnt lgkmcnt(7)
	v_mfma_f32_32x32x16_bf16 v[80:95], v[170:173], v[110:113], v[80:95]
	ds_read_b128 v[170:173], v159 offset:4608
	v_exp_f32_e32 v32, v40
	v_exp_f32_e32 v39, v57
	v_exp_f32_e32 v33, v41
	v_exp_f32_e32 v56, v60
	s_waitcnt lgkmcnt(3)
	v_mfma_f32_32x32x16_bf16 v[64:79], v[138:141], v[102:105], v[64:79]
	ds_read_b64_tr_b16 v[138:139], v154 offset:31744
	ds_read_b64_tr_b16 v[140:141], v154 offset:32256
	v_exp_f32_e32 v40, v44
	v_exp_f32_e32 v57, v61
	v_exp_f32_e32 v41, v45
	v_exp_f32_e32 v44, v62
	s_waitcnt lgkmcnt(4)
	v_mfma_f32_32x32x16_bf16 v[64:79], v[142:145], v[106:109], v[64:79]
	ds_read_b64_tr_b16 v[142:143], v154 offset:30720
	ds_read_b64_tr_b16 v[144:145], v154 offset:31232
	v_exp_f32_e32 v45, v63
	v_add_f32_e32 v46, v36, v37
	v_add_f32_e32 v47, v130, v48
	v_add_f32_e32 v46, v131, v46
	v_add_f32_e32 v47, v49, v47
	v_add_f32_e32 v46, v132, v46
	s_waitcnt lgkmcnt(5)
	v_mfma_f32_32x32x16_bf16 v[64:79], v[166:169], v[110:113], v[64:79]
	v_add_f32_e32 v47, v50, v47
	v_add_f32_e32 v46, v133, v46
	v_add_f32_e32 v47, v51, v47
	v_add_f32_e32 v46, v34, v46
	v_add_f32_e32 v47, v35, v47
	v_add_f32_e32 v46, v42, v46
	v_add_f32_e32 v47, v43, v47
	s_waitcnt lgkmcnt(4)
	v_mfma_f32_32x32x16_bf16 v[64:79], v[170:173], v[98:101], v[64:79]
	v_add_f32_e32 v46, v134, v46
	v_add_f32_e32 v47, v135, v47
	v_add_f32_e32 v46, v136, v46
	v_add_f32_e32 v47, v137, v47
	v_add_f32_e32 v46, v54, v46
	v_add_f32_e32 v47, v55, v47
	v_add_f32_e32 v46, v52, v46
	v_mfma_f32_32x32x16_bf16 v[16:31], v[192:195], v[126:129], v[16:31]
	v_add_f32_e32 v47, v53, v47
	v_add_f32_e32 v46, v38, v46
	v_add_f32_e32 v47, v32, v47
	v_add_f32_e32 v46, v39, v46
	v_add_f32_e32 v47, v33, v47
	v_add_f32_e32 v46, v56, v46
	v_add_f32_e32 v47, v40, v47
	v_mfma_f32_32x32x16_bf16 v[16:31], v[196:199], v[122:125], v[16:31]
	v_add_f32_e32 v46, v57, v46
	v_add_f32_e32 v47, v41, v47
	v_add_f32_e32 v46, v44, v46
	v_add_f32_e32 v47, v45, v47
	v_add_f32_e32 v46, v46, v47
	s_waitcnt lgkmcnt(2)
	v_mfma_f32_32x32x16_bf16 v[0:15], v[138:141], v[122:125], v[0:15]
	s_waitcnt lgkmcnt(0)
	v_mfma_f32_32x32x16_bf16 v[0:15], v[142:145], v[126:129], v[0:15]
	v_cmp_lt_f32_e32 vcc, s1, v46
	v_mov_b32_e32 v154, v46
	s_cbranch_vccnz .LBB0_381
	v_cvt_pk_bf16_f32 v130, v130, v131
	v_cvt_pk_bf16_f32 v131, v132, v133
	v_cvt_pk_bf16_f32 v132, v134, v135
	v_cvt_pk_bf16_f32 v133, v136, v137
	v_cvt_pk_bf16_f32 v122, v48, v49
	v_cvt_pk_bf16_f32 v123, v50, v51
	v_cvt_pk_bf16_f32 v124, v36, v37
	v_cvt_pk_bf16_f32 v125, v52, v53
	v_cvt_pk_bf16_f32 v134, v38, v39
	v_cvt_pk_bf16_f32 v135, v54, v55
	v_cvt_pk_bf16_f32 v136, v56, v57
	v_cvt_pk_bf16_f32 v137, v44, v45
	v_cvt_pk_bf16_f32 v126, v32, v33
	v_cvt_pk_bf16_f32 v127, v34, v35
	v_cvt_pk_bf16_f32 v128, v40, v41
	v_cvt_pk_bf16_f32 v129, v42, v43
	v_cndmask_b32_e64 v32, 0, 1, s[20:21]
	v_cmp_ne_u32_e64 s[2:3], 1, v32
	s_andn2_b64 vcc, exec, s[20:21]
	s_cbranch_vccnz .LBB0_368

.LBB0_368:
	s_add_i32 s20, s27, 0x2000
	s_cmpk_lg_i32 s27, 0x4000
	s_cselect_b32 s27, s20, 0
	v_add_u32_e32 v32, s27, v158
	s_waitcnt vmcnt(0)
	ds_write_b128 v32, v[118:121] offset:28672
	s_add_i32 s101, s27, 0xffffe000
	s_cmp_lg_u32 s27, 0
	s_cselect_b32 s101, s101, 0x4000
	v_add_u32_e32 v250, s101, v164
	ds_read_b64_tr_b16 v[234:235], v250 offset:29696
	ds_read_b64_tr_b16 v[236:237], v250 offset:30208
	ds_read_b64_tr_b16 v[238:239], v250 offset:33792
	ds_read_b64_tr_b16 v[240:241], v250 offset:34304
	s_waitcnt lgkmcnt(4)
	s_barrier
	s_cmp_lt_u32 s28, s22
	s_cselect_b64 s[20:21], -1, 0
	s_cmp_ge_u32 s28, s22
	s_cbranch_scc1 .LBB0_370
	global_load_dwordx4 v[114:117], v[152:153], off

.LBB0_372:
	s_add_i32 s2, s27, 0xffffe000
	s_cmp_lg_u32 s27, 0
	s_cselect_b32 s2, s2, 0x4000
	ds_read_b128 v[138:141], v159 offset:14336
	ds_read_b128 v[166:169], v159 offset:14368
	ds_read_b128 v[170:173], v159 offset:14400
	ds_read_b128 v[174:177], v159 offset:14432
	s_waitcnt lgkmcnt(4)
	v_mfma_f32_32x32x16_bf16 v[0:15], v[234:237], v[134:137], v[0:15]
	v_xor_b32_e32 v32, 0x80000000, v162
	v_mov_b32_e32 v33, v32
	v_mov_b64_e32 v[34:35], v[32:33]
	v_mov_b64_e32 v[36:37], v[32:33]
	v_mov_b64_e32 v[38:39], v[32:33]
	v_mov_b64_e32 v[40:41], v[32:33]
	v_mov_b64_e32 v[42:43], v[32:33]
	v_mfma_f32_32x32x16_bf16 v[16:31], v[238:241], v[134:137], v[16:31]
	v_mov_b64_e32 v[44:45], v[32:33]
	v_mov_b64_e32 v[46:47], v[32:33]
	v_add_f32_e64 v142, v154, v155
	v_add_f32_e64 v143, v155, v154
	v_add_u32_e32 v143, s2, v164
	ds_read_b64_tr_b16 v[192:193], v143 offset:30720
	ds_read_b64_tr_b16 v[194:195], v143 offset:31232
	ds_read_b64_tr_b16 v[196:197], v143 offset:34816
	ds_read_b64_tr_b16 v[198:199], v143 offset:35328
	ds_read_b64_tr_b16 v[200:201], v143 offset:35840
	ds_read_b64_tr_b16 v[202:203], v143 offset:36352
	v_exp_f32_e32 v80, v80
	v_exp_f32_e32 v64, v64
	v_exp_f32_e32 v81, v81
	v_exp_f32_e32 v65, v65
	v_exp_f32_e32 v82, v82
	s_waitcnt lgkmcnt(9)
	v_mfma_f32_32x32x16_bf16 v[48:63], v[138:141], v[98:101], v[32:47]
	ds_read_b128 v[138:141], v159 offset:18976
	v_exp_f32_e32 v66, v66
	v_exp_f32_e32 v83, v83
	v_exp_f32_e32 v67, v67
	v_exp_f32_e32 v84, v84
	s_waitcnt lgkmcnt(9)
	v_mfma_f32_32x32x16_bf16 v[48:63], v[166:169], v[102:105], v[48:63]
	ds_read_b128 v[166:169], v159 offset:19008
	v_exp_f32_e32 v68, v68
	v_exp_f32_e32 v85, v85
	v_exp_f32_e32 v69, v69
	v_exp_f32_e32 v70, v70
	s_waitcnt lgkmcnt(9)
	v_mfma_f32_32x32x16_bf16 v[48:63], v[170:173], v[106:109], v[48:63]
	ds_read_b128 v[170:173], v159 offset:19040
	v_exp_f32_e32 v71, v71
	v_exp_f32_e32 v72, v72
	v_exp_f32_e32 v73, v73
	v_exp_f32_e32 v74, v74
	s_waitcnt lgkmcnt(9)
	v_mfma_f32_32x32x16_bf16 v[48:63], v[174:177], v[110:113], v[48:63]
	ds_read_b128 v[174:177], v159 offset:18944
	v_exp_f32_e32 v75, v75
	v_exp_f32_e32 v76, v76
	v_exp_f32_e32 v77, v77
	v_exp_f32_e32 v78, v78
	s_waitcnt lgkmcnt(3)
	v_mfma_f32_32x32x16_bf16 v[32:47], v[138:141], v[102:105], v[32:47]
	ds_read_b64_tr_b16 v[138:139], v143 offset:31744
	ds_read_b64_tr_b16 v[140:141], v143 offset:32256
	v_exp_f32_e32 v79, v79
	v_exp_f32_e32 v134, v86
	v_exp_f32_e32 v135, v87
	v_exp_f32_e32 v86, v88
	s_waitcnt lgkmcnt(4)
	v_mfma_f32_32x32x16_bf16 v[32:47], v[166:169], v[106:109], v[32:47]
	ds_read_b64_tr_b16 v[166:167], v143 offset:28672
	ds_read_b64_tr_b16 v[168:169], v143 offset:29184
	v_exp_f32_e32 v87, v89
	v_exp_f32_e32 v88, v90
	v_exp_f32_e32 v89, v91
	v_exp_f32_e32 v90, v92
	s_waitcnt lgkmcnt(5)
	v_mfma_f32_32x32x16_bf16 v[32:47], v[170:173], v[110:113], v[32:47]
	ds_read_b64_tr_b16 v[170:171], v143 offset:32768
	ds_read_b64_tr_b16 v[172:173], v143 offset:33280
	v_exp_f32_e32 v91, v93
	v_exp_f32_e32 v92, v94
	v_exp_f32_e32 v93, v95
	v_add_f32_e32 v94, v80, v64
	s_waitcnt lgkmcnt(6)
	v_mfma_f32_32x32x16_bf16 v[32:47], v[174:177], v[98:101], v[32:47]
	v_add_f32_e32 v95, v81, v65
	v_add_f32_e32 v94, v82, v94
	v_add_f32_e32 v95, v66, v95
	v_add_f32_e32 v94, v83, v94
	v_add_f32_e32 v95, v67, v95
	v_add_f32_e32 v94, v84, v94
	v_add_f32_e32 v95, v68, v95
	v_mfma_f32_32x32x16_bf16 v[0:15], v[192:195], v[122:125], v[0:15]
	v_add_f32_e32 v94, v85, v94
	v_add_f32_e32 v95, v69, v95
	v_add_f32_e32 v94, v70, v94
	v_add_f32_e32 v95, v71, v95
	v_add_f32_e32 v94, v72, v94
	v_add_f32_e32 v95, v73, v95
	v_add_f32_e32 v94, v74, v94
	v_mfma_f32_32x32x16_bf16 v[16:31], v[196:199], v[122:125], v[16:31]
	v_add_f32_e32 v95, v75, v95
	v_add_f32_e32 v94, v76, v94
	v_add_f32_e32 v95, v77, v95
	v_add_f32_e32 v94, v78, v94
	v_add_f32_e32 v95, v79, v95
	v_add_f32_e32 v94, v134, v94
	v_add_f32_e32 v95, v135, v95
	v_mfma_f32_32x32x16_bf16 v[16:31], v[200:203], v[126:129], v[16:31]
	v_add_f32_e32 v94, v86, v94
	v_add_f32_e32 v95, v87, v95
	v_add_f32_e32 v94, v88, v94
	v_add_f32_e32 v95, v89, v95
	v_add_f32_e32 v94, v90, v94
	v_add_f32_e32 v95, v91, v95
	v_add_f32_e32 v94, v92, v94
	s_waitcnt lgkmcnt(4)
	v_mfma_f32_32x32x16_bf16 v[0:15], v[138:141], v[126:129], v[0:15]
	v_add_f32_e32 v95, v93, v95
	v_add_f32_e32 v94, v94, v95
	s_waitcnt lgkmcnt(2)
	v_mfma_f32_32x32x16_bf16 v[0:15], v[166:169], v[130:133], v[0:15]
	s_waitcnt lgkmcnt(0)
	v_mfma_f32_32x32x16_bf16 v[16:31], v[170:173], v[130:133], v[16:31]
	v_cmp_lt_f32_e32 vcc, s1, v94
	s_cbranch_vccnz .LBB0_382
	v_cvt_pk_bf16_f32 v130, v80, v81
	v_cvt_pk_bf16_f32 v131, v82, v83
	v_cvt_pk_bf16_f32 v132, v84, v85
	v_cvt_pk_bf16_f32 v133, v134, v135
	v_cvt_pk_bf16_f32 v126, v64, v65
	v_cvt_pk_bf16_f32 v127, v66, v67
	v_cvt_pk_bf16_f32 v128, v68, v69
	v_cvt_pk_bf16_f32 v129, v70, v71
	v_cvt_pk_bf16_f32 v134, v86, v87
	v_cvt_pk_bf16_f32 v135, v88, v89
	v_cvt_pk_bf16_f32 v136, v90, v91
	v_cvt_pk_bf16_f32 v137, v92, v93
	v_cvt_pk_bf16_f32 v122, v72, v73
	v_cvt_pk_bf16_f32 v123, v74, v75
	v_cvt_pk_bf16_f32 v124, v76, v77
	v_cvt_pk_bf16_f32 v125, v78, v79
	s_mov_b32 s28, s48
	s_andn2_b64 vcc, exec, s[20:21]
	s_cbranch_vccnz .LBB0_375

; template <int KIND>
; DI void attn_unit(const Frame& F, int qrow0, int head, int ctx_row0, int lat_row0, int ntiles) {
;     ...
;     for (int t2 = 1; t2 < ntiles - 1; t2 += 2) {
;         { const int t = t2; ATT_BODY(t, kreg, vreg, rreg, kreg, vreg, rreg, n0, n1, s0, s1, pfb, pfa, 1, 1); }
;         { const int t = t2 + 1; ATT_BODY(t, kreg, vreg, rreg, kreg, vreg, rreg, s0, s1, n0, n1, pfa, pfb, 1, 1); }
;     }
.LBB0_379:
	v_add_u32_e32 v250, s27, v164
	ds_read_b64_tr_b16 v[234:235], v250 offset:28672
	ds_read_b64_tr_b16 v[236:237], v250 offset:29184
	ds_read_b64_tr_b16 v[238:239], v250 offset:32768
	ds_read_b64_tr_b16 v[240:241], v250 offset:33280
	ds_read_b64_tr_b16 v[242:243], v250 offset:29696
	ds_read_b64_tr_b16 v[244:245], v250 offset:30208
	ds_read_b64_tr_b16 v[246:247], v250 offset:33792
	ds_read_b64_tr_b16 v[248:249], v250 offset:34304
	s_waitcnt lgkmcnt(8)
	s_barrier
	s_cmpk_lg_i32 s27, 0x4000
	v_mov_b32_e32 v143, v94
	s_cselect_b32 s27, s18, 0
	s_mov_b64 s[2:3], 0x8000
	s_addk_i32 s24, 0x80
	s_addk_i32 s25, 0x80
	v_pk_add_f32 v[64:65], v[94:95], v[142:143]
	v_lshl_add_u64 v[152:153], v[152:153], 0, s[2:3]
	s_cmp_lt_u32 s26, s16
	v_add_u32_e32 v165, 0x80, v165
	s_cbranch_scc0 .LBB0_383
	v_mov_b32_e32 v155, v64
	s_mov_b32 s28, s26
	s_branch .LBB0_363

; template <int KIND>
; DI void attn_unit(const Frame& F, int qrow0, int head, int ctx_row0, int lat_row0, int ntiles) {
;     ...
;     { const int t = ntiles - 1; ATT_BODY(t, kreg, vreg, rreg, kreg, vreg, rreg, n0, n1, s0, s1, pfb, pfa, 1, 0); }
;     ATT_PV(pfb, lds + ATT_VB + (vs_c == 0 ? 2 * ATT_VBUF : vs_c - ATT_VBUF));
.LBB0_383:
	s_waitcnt lgkmcnt(0)
	s_add_i32 s2, s27, 0xffffe000
	s_cmp_lg_u32 s27, 0
	s_cselect_b32 s2, s2, 0x4000
	s_add_i32 s2, s2, 0
	v_add_u32_e32 v65, s2, v163
	ds_read_b64_tr_b16 v[66:67], v65 offset:28672
	ds_read_b64_tr_b16 v[68:69], v65 offset:29184
	ds_read_b64_tr_b16 v[70:71], v65 offset:29696
	ds_read_b64_tr_b16 v[72:73], v65 offset:30208
	v_exp_f32_e32 v32, v32
	v_exp_f32_e32 v33, v33
	s_waitcnt lgkmcnt(2)
	v_mfma_f32_32x32x16_bf16 v[0:15], v[66:69], v[130:133], v[0:15]
	ds_read_b64_tr_b16 v[66:67], v65 offset:32768
	ds_read_b64_tr_b16 v[68:69], v65 offset:33280
	ds_read_b64_tr_b16 v[74:75], v65 offset:33792
	ds_read_b64_tr_b16 v[76:77], v65 offset:34304
	v_exp_f32_e32 v34, v34
	v_exp_f32_e32 v35, v35
	ds_read_b64_tr_b16 v[78:79], v65 offset:30720
	ds_read_b64_tr_b16 v[80:81], v65 offset:31232
	ds_read_b64_tr_b16 v[82:83], v65 offset:31744
	ds_read_b64_tr_b16 v[84:85], v65 offset:32256
	ds_read_b64_tr_b16 v[86:87], v65 offset:34816
	ds_read_b64_tr_b16 v[88:89], v65 offset:35328
	ds_read_b64_tr_b16 v[90:91], v65 offset:35840
	ds_read_b64_tr_b16 v[92:93], v65 offset:36352
	s_waitcnt lgkmcnt(10)
	v_mfma_f32_32x32x16_bf16 v[16:31], v[66:69], v[130:133], v[16:31]
	v_exp_f32_e32 v66, v36
	v_exp_f32_e32 v67, v37
	v_exp_f32_e32 v36, v40
	v_exp_f32_e32 v37, v41
	v_mov_b32_e32 v40, v32
	v_exp_f32_e32 v68, v38
	v_exp_f32_e32 v69, v39
	v_mfma_f32_32x32x16_bf16 v[0:15], v[70:73], v[134:137], v[0:15]
	v_exp_f32_e32 v70, v48
	v_exp_f32_e32 v71, v49
	v_exp_f32_e32 v72, v50
	v_exp_f32_e32 v73, v51
	v_mov_b32_e32 v41, v70
	v_pk_add_f32 v[40:41], v[40:41], 0 op_sel_hi:[1,0]
	v_exp_f32_e32 v50, v56
	s_waitcnt lgkmcnt(8)
	v_mfma_f32_32x32x16_bf16 v[16:31], v[74:77], v[134:137], v[16:31]
	v_exp_f32_e32 v74, v52
	v_exp_f32_e32 v75, v53
	v_exp_f32_e32 v76, v54
	v_exp_f32_e32 v77, v55
	v_exp_f32_e32 v54, v44
	v_exp_f32_e32 v55, v45
	v_mov_b32_e32 v44, v33
	v_mov_b32_e32 v45, v71
	v_pk_add_f32 v[40:41], v[44:45], v[40:41]
	v_mov_b32_e32 v44, v34
	v_mov_b32_e32 v45, v72
	s_waitcnt lgkmcnt(2)
	v_mfma_f32_32x32x16_bf16 v[16:31], v[86:89], v[126:129], v[16:31]
	v_add_f32_e64 v40, v44, v40
	v_add_f32_e64 v41, v45, v41
	v_mov_b32_e32 v44, v35
	v_mov_b32_e32 v45, v73
	v_add_f32_e64 v40, v44, v40
	v_add_f32_e64 v41, v45, v41
	v_mov_b32_e32 v44, v66
	v_mov_b32_e32 v45, v74
	v_exp_f32_e32 v51, v57
	v_mfma_f32_32x32x16_bf16 v[0:15], v[78:81], v[126:129], v[0:15]
	v_add_f32_e64 v40, v44, v40
	v_add_f32_e64 v41, v45, v41
	v_mov_b32_e32 v44, v67
	v_mov_b32_e32 v45, v75
	v_exp_f32_e32 v52, v58
	v_exp_f32_e32 v38, v42
	v_pk_add_f32 v[40:41], v[44:45], v[40:41]
	v_mov_b32_e32 v44, v68
	v_mov_b32_e32 v45, v76
	v_exp_f32_e32 v53, v59
	v_exp_f32_e32 v39, v43
	v_pk_add_f32 v[40:41], v[44:45], v[40:41]
	v_mov_b32_e32 v44, v69
	v_mov_b32_e32 v45, v77
	v_exp_f32_e32 v42, v60
	v_pk_add_f32 v[40:41], v[44:45], v[40:41]
	v_mov_b32_e32 v44, v36
	v_mov_b32_e32 v45, v50
	v_exp_f32_e32 v43, v61
	v_pk_add_f32 v[40:41], v[44:45], v[40:41]
	v_mov_b32_e32 v44, v37
	v_mov_b32_e32 v45, v51
	v_exp_f32_e32 v58, v62
	v_exp_f32_e32 v56, v46
	v_pk_add_f32 v[40:41], v[44:45], v[40:41]
	v_mov_b32_e32 v44, v38
	v_mov_b32_e32 v45, v52
	v_exp_f32_e32 v59, v63
	v_exp_f32_e32 v57, v47
	s_waitcnt lgkmcnt(0)
	v_mfma_f32_32x32x16_bf16 v[16:31], v[90:93], v[122:125], v[16:31]
	v_add_f32_e64 v40, v44, v40
	v_add_f32_e64 v41, v45, v41
	v_mov_b32_e32 v44, v39
	v_mov_b32_e32 v45, v53
	v_add_f32_e64 v40, v44, v40
	v_add_f32_e64 v41, v45, v41
	v_mov_b32_e32 v44, v54
	v_mov_b32_e32 v45, v42
	v_pk_add_f32 v[40:41], v[44:45], v[40:41]
	v_mfma_f32_32x32x16_bf16 v[0:15], v[82:85], v[122:125], v[0:15]
	v_mov_b32_e32 v44, v55
	v_mov_b32_e32 v45, v43
	v_add_f32_e64 v40, v44, v40
	v_add_f32_e64 v41, v45, v41
	v_mov_b32_e32 v44, v56
	v_mov_b32_e32 v45, v58
	v_pk_add_f32 v[40:41], v[44:45], v[40:41]
	v_mov_b32_e32 v44, v57
	v_mov_b32_e32 v45, v59
	v_pk_add_f32 v[40:41], v[44:45], v[40:41]
	s_nop 0
	v_pk_add_f32 v[48:49], v[40:41], v[40:41] op_sel:[0,1] op_sel_hi:[1,0]
	s_nop 0
	v_cmp_lt_f32_e32 vcc, s1, v48
	s_cbranch_vccnz .LBB0_450
	v_cvt_pk_bf16_f32 v44, v70, v71
	v_cvt_pk_bf16_f32 v45, v72, v73
	v_cvt_pk_bf16_f32 v46, v74, v75
	v_cvt_pk_bf16_f32 v47, v76, v77
	v_cvt_pk_bf16_f32 v32, v32, v33
	v_cvt_pk_bf16_f32 v33, v34, v35
	v_cvt_pk_bf16_f32 v34, v66, v67
	v_cvt_pk_bf16_f32 v35, v68, v69
	v_cvt_pk_bf16_f32 v40, v50, v51
	v_cvt_pk_bf16_f32 v41, v52, v53
	v_cvt_pk_bf16_f32 v42, v42, v43
	v_cvt_pk_bf16_f32 v43, v58, v59
	v_cvt_pk_bf16_f32 v36, v36, v37
	v_cvt_pk_bf16_f32 v37, v38, v39
	v_cvt_pk_bf16_f32 v38, v54, v55
	v_cvt_pk_bf16_f32 v39, v56, v57

.LBB0_423:
	v_lshl_add_u64 v[164:165], v[154:155], 0, s[44:45]
	v_add_co_u32_e32 v64, vcc, 0xa300000, v164
	s_add_i32 s4, s27, 0xffffe000
	s_nop 0
	v_addc_co_u32_e32 v65, vcc, 0, v165, vcc
	global_load_dwordx4 v[130:133], v[64:65], off
	s_cmp_lg_u32 s27, 0
	s_cselect_b32 s4, s4, 0x4000
	v_add_u32_e32 v160, s4, v174
	ds_read_b128 v[188:191], v170
	ds_read_b128 v[192:195], v170 offset:32
	ds_read_b128 v[196:199], v170 offset:64
	ds_read_b128 v[200:203], v170 offset:96
	ds_read_b128 v[204:207], v171 offset:9216
	ds_read_b128 v[208:211], v171 offset:9248
	ds_read_b64_tr_b16 v[226:227], v160 offset:31744
	ds_read_b64_tr_b16 v[228:229], v160 offset:32256
	ds_read_b64_tr_b16 v[230:231], v160 offset:35840
	ds_read_b64_tr_b16 v[232:233], v160 offset:36352
	s_waitcnt lgkmcnt(10)
	v_mfma_f32_32x32x16_bf16 v[16:31], v[234:237], v[142:145], v[16:31]
	v_xor_b32_e32 v64, 0x80000000, v172
	v_mov_b32_e32 v65, v64
	v_mov_b64_e32 v[66:67], v[64:65]
	v_mov_b64_e32 v[68:69], v[64:65]
	v_mov_b64_e32 v[70:71], v[64:65]
	v_mov_b64_e32 v[72:73], v[64:65]
	v_mfma_f32_32x32x16_bf16 v[0:15], v[238:241], v[142:145], v[0:15]
	v_mov_b64_e32 v[74:75], v[64:65]
	v_mov_b64_e32 v[76:77], v[64:65]
	v_mov_b64_e32 v[78:79], v[64:65]
	v_exp_f32_e32 v34, v34
	v_exp_f32_e32 v35, v35
	v_mfma_f32_32x32x16_bf16 v[16:31], v[242:245], v[146:149], v[16:31]
	v_exp_f32_e32 v142, v48
	v_exp_f32_e32 v48, v32
	v_exp_f32_e32 v143, v49
	v_mfma_f32_32x32x16_bf16 v[0:15], v[246:249], v[146:149], v[0:15]
	v_exp_f32_e32 v49, v33
	v_exp_f32_e32 v144, v50
	v_exp_f32_e32 v145, v51
	s_waitcnt lgkmcnt(9)
	v_mfma_f32_32x32x16_bf16 v[80:95], v[188:191], v[98:101], v[64:79]
	ds_read_b128 v[188:191], v170 offset:4640
	v_exp_f32_e32 v50, v36
	v_exp_f32_e32 v32, v40
	v_exp_f32_e32 v33, v41
	s_waitcnt lgkmcnt(9)
	v_mfma_f32_32x32x16_bf16 v[80:95], v[192:195], v[102:105], v[80:95]
	ds_read_b128 v[192:195], v170 offset:4672
	v_exp_f32_e32 v40, v46
	v_exp_f32_e32 v41, v47
	v_exp_f32_e32 v51, v37
	s_waitcnt lgkmcnt(9)
	v_mfma_f32_32x32x16_bf16 v[80:95], v[196:199], v[106:109], v[80:95]
	ds_read_b128 v[196:199], v170 offset:4704
	v_exp_f32_e32 v146, v52
	v_exp_f32_e32 v147, v53
	v_exp_f32_e32 v52, v56
	s_waitcnt lgkmcnt(9)
	v_mfma_f32_32x32x16_bf16 v[80:95], v[200:203], v[110:113], v[80:95]
	ds_read_b128 v[200:203], v171 offset:11776
	v_exp_f32_e32 v53, v57
	v_exp_f32_e32 v56, v58
	v_exp_f32_e32 v57, v59
	s_waitcnt lgkmcnt(9)
	v_mfma_f32_32x32x16_bf16 v[80:95], v[204:207], v[114:117], v[80:95]
	ds_read_b128 v[204:207], v171 offset:11808
	v_exp_f32_e32 v148, v54
	v_exp_f32_e32 v54, v38
	v_exp_f32_e32 v149, v55
	s_waitcnt lgkmcnt(9)
	v_mfma_f32_32x32x16_bf16 v[80:95], v[208:211], v[118:121], v[80:95]
	ds_read_b128 v[208:211], v170 offset:4608
	v_exp_f32_e32 v55, v39
	v_exp_f32_e32 v36, v42
	v_exp_f32_e32 v37, v43
	s_waitcnt lgkmcnt(5)
	v_mfma_f32_32x32x16_bf16 v[64:79], v[188:191], v[102:105], v[64:79]
	v_exp_f32_e32 v42, v60
	v_exp_f32_e32 v38, v44
	v_exp_f32_e32 v43, v61
	s_waitcnt lgkmcnt(4)
	v_mfma_f32_32x32x16_bf16 v[64:79], v[192:195], v[106:109], v[64:79]
	v_exp_f32_e32 v39, v45
	v_exp_f32_e32 v44, v62
	v_exp_f32_e32 v45, v63
	s_waitcnt lgkmcnt(3)
	v_mfma_f32_32x32x16_bf16 v[64:79], v[196:199], v[110:113], v[64:79]
	v_add_f32_e32 v46, v34, v35
	v_add_f32_e32 v47, v142, v48
	v_add_f32_e32 v46, v143, v46
	v_add_f32_e32 v47, v49, v47
	v_add_f32_e32 v46, v144, v46
	v_add_f32_e32 v47, v145, v47
	s_waitcnt lgkmcnt(2)
	v_mfma_f32_32x32x16_bf16 v[64:79], v[200:203], v[114:117], v[64:79]
	v_add_f32_e32 v46, v50, v46
	v_add_f32_e32 v47, v32, v47
	v_add_f32_e32 v46, v33, v46
	v_add_f32_e32 v47, v40, v47
	v_add_f32_e32 v46, v41, v46
	v_add_f32_e32 v47, v51, v47
	s_waitcnt lgkmcnt(1)
	v_mfma_f32_32x32x16_bf16 v[64:79], v[204:207], v[118:121], v[64:79]
	ds_read_b64_tr_b16 v[204:205], v160 offset:30720
	ds_read_b64_tr_b16 v[206:207], v160 offset:31232
	v_add_f32_e32 v46, v146, v46
	v_add_f32_e32 v47, v147, v47
	v_add_f32_e32 v46, v52, v46
	v_add_f32_e32 v47, v53, v47
	v_add_f32_e32 v46, v56, v46
	v_add_f32_e32 v47, v57, v47
	s_waitcnt lgkmcnt(2)
	v_mfma_f32_32x32x16_bf16 v[64:79], v[208:211], v[98:101], v[64:79]
	ds_read_b64_tr_b16 v[208:209], v160 offset:34816
	ds_read_b64_tr_b16 v[210:211], v160 offset:35328
	v_add_f32_e32 v46, v148, v46
	v_add_f32_e32 v47, v54, v47
	v_add_f32_e32 v46, v149, v46
	v_add_f32_e32 v47, v55, v47
	v_add_f32_e32 v46, v36, v46
	v_add_f32_e32 v47, v37, v47
	v_mfma_f32_32x32x16_bf16 v[16:31], v[226:229], v[138:141], v[16:31]
	v_add_f32_e32 v46, v42, v46
	v_add_f32_e32 v47, v38, v47
	v_add_f32_e32 v46, v43, v46
	v_add_f32_e32 v47, v39, v47
	v_add_f32_e32 v46, v44, v46
	v_add_f32_e32 v47, v45, v47
	v_mfma_f32_32x32x16_bf16 v[0:15], v[230:233], v[138:141], v[0:15]
	v_add_f32_e32 v46, v46, v47
	s_waitcnt lgkmcnt(2)
	v_mfma_f32_32x32x16_bf16 v[16:31], v[204:207], v[134:137], v[16:31]
	s_waitcnt lgkmcnt(0)
	v_mfma_f32_32x32x16_bf16 v[0:15], v[208:211], v[134:137], v[0:15]
	v_cmp_lt_f32_e32 vcc, s1, v46
	v_mov_b32_e32 v160, v46
	s_cbranch_vccnz .LBB0_445
	v_cvt_pk_bf16_f32 v142, v142, v143
	v_cvt_pk_bf16_f32 v143, v144, v145
	v_cvt_pk_bf16_f32 v144, v146, v147
	v_cvt_pk_bf16_f32 v145, v148, v149
	v_cvt_pk_bf16_f32 v134, v48, v49
	v_cvt_pk_bf16_f32 v135, v34, v35
	v_cvt_pk_bf16_f32 v136, v50, v51
	v_cvt_pk_bf16_f32 v137, v54, v55
	v_cvt_pk_bf16_f32 v146, v52, v53
	v_cvt_pk_bf16_f32 v147, v56, v57
	v_cvt_pk_bf16_f32 v148, v42, v43
	v_cvt_pk_bf16_f32 v149, v44, v45
	v_cvt_pk_bf16_f32 v138, v32, v33
	v_cvt_pk_bf16_f32 v139, v36, v37
	v_cvt_pk_bf16_f32 v140, v38, v39
	v_cvt_pk_bf16_f32 v141, v40, v41
	v_cndmask_b32_e64 v32, 0, 1, s[20:21]
	v_cmp_ne_u32_e64 s[4:5], 1, v32
	s_andn2_b64 vcc, exec, s[20:21]
	s_cbranch_vccnz .LBB0_428

.LBB0_428:
	s_add_i32 s8, s27, 0x2000
	s_cmpk_lg_i32 s27, 0x4000
	s_cselect_b32 s27, s8, 0
	v_add_u32_e32 v32, s27, v169
	s_waitcnt vmcnt(0)
	ds_write_b128 v32, v[130:133] offset:28672
	s_add_i32 s101, s27, 0xffffe000
	s_cmp_lg_u32 s27, 0
	s_cselect_b32 s101, s101, 0x4000
	v_add_u32_e32 v250, s101, v174
	ds_read_b64_tr_b16 v[234:235], v250 offset:28672
	ds_read_b64_tr_b16 v[236:237], v250 offset:29184
	ds_read_b64_tr_b16 v[238:239], v250 offset:32768
	ds_read_b64_tr_b16 v[240:241], v250 offset:33280
	ds_read_b64_tr_b16 v[242:243], v250 offset:29696
	ds_read_b64_tr_b16 v[244:245], v250 offset:30208
	ds_read_b64_tr_b16 v[246:247], v250 offset:33792
	ds_read_b64_tr_b16 v[248:249], v250 offset:34304
	s_waitcnt lgkmcnt(8)
	s_barrier
	s_cmp_lt_u32 s28, s24
	s_cselect_b64 s[20:21], -1, 0
	s_cmp_ge_u32 s28, s24
	s_cbranch_scc1 .LBB0_432
	v_add_co_u32_e32 v32, vcc, 0x9120000, v164
	s_nop 1
	v_addc_co_u32_e32 v33, vcc, 0, v165, vcc
	global_load_dwordx4 v[126:129], v[32:33], off
	s_and_saveexec_b64 s[8:9], s[2:3]
	s_cbranch_execz .LBB0_431
	v_lshl_add_u64 v[32:33], v[158:159], 0, s[44:45]
	global_load_dwordx4 v[122:125], v[32:33], off

.LBB0_434:
	s_add_i32 s4, s27, 0xffffe000
	s_cmp_lg_u32 s27, 0
	s_cselect_b32 s4, s4, 0x4000
	ds_read_b128 v[162:165], v170 offset:14336
	ds_read_b128 v[188:191], v170 offset:14368
	ds_read_b128 v[192:195], v170 offset:14400
	ds_read_b128 v[196:199], v170 offset:14432
	ds_read_b128 v[200:203], v171 offset:23552
	ds_read_b128 v[204:207], v171 offset:23584
	s_waitcnt lgkmcnt(6)
	v_mfma_f32_32x32x16_bf16 v[16:31], v[234:237], v[142:145], v[16:31]
	v_xor_b32_e32 v32, 0x80000000, v172
	v_mov_b32_e32 v33, v32
	v_mov_b64_e32 v[34:35], v[32:33]
	v_mov_b64_e32 v[36:37], v[32:33]
	v_mov_b64_e32 v[38:39], v[32:33]
	v_mov_b64_e32 v[40:41], v[32:33]
	v_mfma_f32_32x32x16_bf16 v[0:15], v[238:241], v[142:145], v[0:15]
	v_mov_b64_e32 v[42:43], v[32:33]
	v_mov_b64_e32 v[44:45], v[32:33]
	v_mov_b64_e32 v[46:47], v[32:33]
	v_pk_add_f32 v[160:161], v[160:161], v[160:161] op_sel:[0,1] op_sel_hi:[1,0]
	v_add_u32_e32 v161, s4, v174
	ds_read_b64_tr_b16 v[208:209], v161 offset:31744
	ds_read_b64_tr_b16 v[210:211], v161 offset:32256
	ds_read_b64_tr_b16 v[226:227], v161 offset:35840
	ds_read_b64_tr_b16 v[228:229], v161 offset:36352
	v_exp_f32_e32 v142, v80
	v_mfma_f32_32x32x16_bf16 v[16:31], v[242:245], v[146:149], v[16:31]
	v_exp_f32_e32 v80, v64
	v_exp_f32_e32 v143, v81
	v_exp_f32_e32 v81, v65
	v_mfma_f32_32x32x16_bf16 v[0:15], v[246:249], v[146:149], v[0:15]
	v_exp_f32_e32 v144, v82
	v_exp_f32_e32 v82, v66
	v_exp_f32_e32 v145, v83
	s_waitcnt lgkmcnt(9)
	v_mfma_f32_32x32x16_bf16 v[48:63], v[162:165], v[98:101], v[32:47]
	ds_read_b128 v[162:165], v170 offset:18976
	v_exp_f32_e32 v83, v67
	v_exp_f32_e32 v64, v72
	v_exp_f32_e32 v65, v73
	s_waitcnt lgkmcnt(9)
	v_mfma_f32_32x32x16_bf16 v[48:63], v[188:191], v[102:105], v[48:63]
	ds_read_b128 v[188:191], v170 offset:19008
	v_exp_f32_e32 v72, v78
	v_exp_f32_e32 v73, v79
	v_exp_f32_e32 v146, v84
	s_waitcnt lgkmcnt(9)
	v_mfma_f32_32x32x16_bf16 v[48:63], v[192:195], v[106:109], v[48:63]
	ds_read_b128 v[192:195], v170 offset:19040
	v_exp_f32_e32 v84, v68
	v_exp_f32_e32 v147, v85
	v_exp_f32_e32 v85, v69
	s_waitcnt lgkmcnt(9)
	v_mfma_f32_32x32x16_bf16 v[48:63], v[196:199], v[110:113], v[48:63]
	ds_read_b128 v[196:199], v171 offset:26112
	v_exp_f32_e32 v148, v86
	v_exp_f32_e32 v86, v70
	v_exp_f32_e32 v149, v87
	s_waitcnt lgkmcnt(9)
	v_mfma_f32_32x32x16_bf16 v[48:63], v[200:203], v[114:117], v[48:63]
	ds_read_b128 v[200:203], v171 offset:26144
	v_exp_f32_e32 v87, v71
	v_exp_f32_e32 v70, v88
	v_exp_f32_e32 v71, v89
	s_waitcnt lgkmcnt(9)
	v_mfma_f32_32x32x16_bf16 v[48:63], v[204:207], v[118:121], v[48:63]
	ds_read_b128 v[204:207], v170 offset:18944
	v_exp_f32_e32 v88, v90
	v_exp_f32_e32 v89, v91
	v_exp_f32_e32 v66, v74
	s_waitcnt lgkmcnt(5)
	v_mfma_f32_32x32x16_bf16 v[32:47], v[162:165], v[102:105], v[32:47]
	v_exp_f32_e32 v67, v75
	v_exp_f32_e32 v74, v92
	v_exp_f32_e32 v68, v76
	s_waitcnt lgkmcnt(4)
	v_mfma_f32_32x32x16_bf16 v[32:47], v[188:191], v[106:109], v[32:47]
	v_exp_f32_e32 v75, v93
	v_exp_f32_e32 v69, v77
	v_exp_f32_e32 v76, v94
	s_waitcnt lgkmcnt(3)
	v_mfma_f32_32x32x16_bf16 v[32:47], v[192:195], v[110:113], v[32:47]
	v_exp_f32_e32 v77, v95
	v_add_f32_e32 v78, v142, v80
	v_add_f32_e32 v79, v143, v81
	v_add_f32_e32 v78, v144, v78
	v_add_f32_e32 v79, v82, v79
	s_waitcnt lgkmcnt(2)
	v_mfma_f32_32x32x16_bf16 v[32:47], v[196:199], v[114:117], v[32:47]
	v_add_f32_e32 v78, v145, v78
	v_add_f32_e32 v79, v83, v79
	v_add_f32_e32 v78, v64, v78
	v_add_f32_e32 v79, v65, v79
	v_add_f32_e32 v78, v72, v78
	v_add_f32_e32 v79, v73, v79
	s_waitcnt lgkmcnt(1)
	v_mfma_f32_32x32x16_bf16 v[32:47], v[200:203], v[118:121], v[32:47]
	ds_read_b64_tr_b16 v[200:201], v161 offset:30720
	ds_read_b64_tr_b16 v[202:203], v161 offset:31232
	v_add_f32_e32 v78, v146, v78
	v_add_f32_e32 v79, v84, v79
	v_add_f32_e32 v78, v147, v78
	v_add_f32_e32 v79, v85, v79
	v_add_f32_e32 v78, v148, v78
	v_add_f32_e32 v79, v86, v79
	s_waitcnt lgkmcnt(2)
	v_mfma_f32_32x32x16_bf16 v[32:47], v[204:207], v[98:101], v[32:47]
	ds_read_b64_tr_b16 v[204:205], v161 offset:34816
	ds_read_b64_tr_b16 v[206:207], v161 offset:35328
	v_add_f32_e32 v78, v149, v78
	v_add_f32_e32 v79, v87, v79
	v_add_f32_e32 v78, v70, v78
	v_add_f32_e32 v79, v71, v79
	v_add_f32_e32 v78, v88, v78
	v_add_f32_e32 v79, v89, v79
	v_mfma_f32_32x32x16_bf16 v[16:31], v[208:211], v[138:141], v[16:31]
	v_add_f32_e32 v78, v66, v78
	v_add_f32_e32 v79, v67, v79
	v_add_f32_e32 v78, v74, v78
	v_add_f32_e32 v79, v68, v79
	v_add_f32_e32 v78, v75, v78
	v_add_f32_e32 v79, v69, v79
	v_mfma_f32_32x32x16_bf16 v[0:15], v[226:229], v[138:141], v[0:15]
	v_add_f32_e32 v78, v76, v78
	v_add_f32_e32 v79, v77, v79
	v_add_f32_e32 v78, v78, v79
	s_waitcnt lgkmcnt(2)
	v_mfma_f32_32x32x16_bf16 v[16:31], v[200:203], v[134:137], v[16:31]
	s_waitcnt lgkmcnt(0)
	v_mfma_f32_32x32x16_bf16 v[0:15], v[204:207], v[134:137], v[0:15]
	v_cmp_lt_f32_e32 vcc, s1, v78
	s_cbranch_vccnz .LBB0_446
	v_cvt_pk_bf16_f32 v142, v142, v143
	v_cvt_pk_bf16_f32 v143, v144, v145
	v_cvt_pk_bf16_f32 v144, v146, v147
	v_cvt_pk_bf16_f32 v145, v148, v149
	v_cvt_pk_bf16_f32 v134, v80, v81
	v_cvt_pk_bf16_f32 v135, v82, v83
	v_cvt_pk_bf16_f32 v136, v84, v85
	v_cvt_pk_bf16_f32 v137, v86, v87
	v_cvt_pk_bf16_f32 v146, v70, v71
	v_cvt_pk_bf16_f32 v147, v88, v89
	v_cvt_pk_bf16_f32 v148, v74, v75
	v_cvt_pk_bf16_f32 v149, v76, v77
	v_cvt_pk_bf16_f32 v138, v64, v65
	v_cvt_pk_bf16_f32 v139, v66, v67
	v_cvt_pk_bf16_f32 v140, v68, v69
	v_cvt_pk_bf16_f32 v141, v72, v73
	s_andn2_b64 vcc, exec, s[20:21]
	s_cbranch_vccnz .LBB0_439

; template <int KIND>
; DI void attn_unit(const Frame& F, int qrow0, int head, int ctx_row0, int lat_row0, int ntiles) {
;     ...
;     bf16x8 pfa[2][2], pfb[2][2];
;     f32x16 s0, s1, n0, n1;
.LBB0_443:
	v_add_u32_e32 v250, s27, v174
	ds_read_b64_tr_b16 v[234:235], v250 offset:28672
	ds_read_b64_tr_b16 v[236:237], v250 offset:29184
	ds_read_b64_tr_b16 v[238:239], v250 offset:32768
	ds_read_b64_tr_b16 v[240:241], v250 offset:33280
	ds_read_b64_tr_b16 v[242:243], v250 offset:29696
	ds_read_b64_tr_b16 v[244:245], v250 offset:30208
	ds_read_b64_tr_b16 v[246:247], v250 offset:33792
	ds_read_b64_tr_b16 v[248:249], v250 offset:34304
	s_waitcnt lgkmcnt(8)
	s_barrier
	s_cmpk_lg_i32 s27, 0x4000
	v_add_f32_e32 v161, v78, v160
	s_cselect_b32 s27, s8, 0
	v_lshl_add_u64 v[152:153], v[152:153], 0, s[74:75]
	v_lshl_add_u64 v[154:155], v[154:155], 0, s[74:75]
	v_lshl_add_u64 v[156:157], v[156:157], 0, s[76:77]
	s_cmp_lt_u32 s26, s25
	v_lshl_add_u64 v[158:159], v[158:159], 0, s[76:77]
	s_cbranch_scc0 .LBB0_447
	s_mov_b32 s28, s26
	s_branch .LBB0_419

.LBB0_447:
	s_waitcnt lgkmcnt(0)
	s_add_i32 s2, s27, 0xffffe000
	s_cmp_lg_u32 s27, 0
	s_cselect_b32 s2, s2, 0x4000
	s_add_i32 s2, s2, 0
	v_add_u32_e32 v92, s2, v173
	ds_read_b64_tr_b16 v[64:65], v92 offset:28672
	ds_read_b64_tr_b16 v[66:67], v92 offset:29184
	ds_read_b64_tr_b16 v[68:69], v92 offset:29696
	ds_read_b64_tr_b16 v[70:71], v92 offset:30208
	v_exp_f32_e32 v32, v32
	v_exp_f32_e32 v33, v33
	s_waitcnt lgkmcnt(2)
	v_mfma_f32_32x32x16_bf16 v[16:31], v[64:67], v[142:145], v[16:31]
	ds_read_b64_tr_b16 v[64:65], v92 offset:32768
	ds_read_b64_tr_b16 v[66:67], v92 offset:33280
	ds_read_b64_tr_b16 v[72:73], v92 offset:33792
	ds_read_b64_tr_b16 v[74:75], v92 offset:34304
	v_exp_f32_e32 v34, v34
	v_exp_f32_e32 v35, v35
	ds_read_b64_tr_b16 v[78:79], v92 offset:30720
	ds_read_b64_tr_b16 v[80:81], v92 offset:31232
	ds_read_b64_tr_b16 v[82:83], v92 offset:31744
	ds_read_b64_tr_b16 v[84:85], v92 offset:32256
	ds_read_b64_tr_b16 v[86:87], v92 offset:34816
	ds_read_b64_tr_b16 v[88:89], v92 offset:35328
	ds_read_b64_tr_b16 v[90:91], v92 offset:35840
	ds_read_b64_tr_b16 v[92:93], v92 offset:36352
	v_and_b32_e32 v76, 63, v166
	v_lshlrev_b32_e32 v77, 3, v167
	s_waitcnt lgkmcnt(10)
	v_mfma_f32_32x32x16_bf16 v[0:15], v[64:67], v[142:145], v[0:15]
	v_exp_f32_e32 v64, v36
	v_exp_f32_e32 v65, v37
	v_exp_f32_e32 v36, v40
	v_exp_f32_e32 v37, v41
	v_mov_b32_e32 v40, v32
	v_exp_f32_e32 v66, v38
	v_exp_f32_e32 v67, v39
	v_mfma_f32_32x32x16_bf16 v[16:31], v[68:71], v[146:149], v[16:31]
	v_exp_f32_e32 v68, v48
	v_exp_f32_e32 v69, v49
	v_exp_f32_e32 v70, v50
	v_exp_f32_e32 v71, v51
	v_mov_b32_e32 v41, v68
	v_exp_f32_e32 v38, v42
	v_exp_f32_e32 v39, v43
	s_waitcnt lgkmcnt(8)
	v_mfma_f32_32x32x16_bf16 v[0:15], v[72:75], v[146:149], v[0:15]
	v_exp_f32_e32 v72, v52
	v_exp_f32_e32 v73, v53
	v_pk_add_f32 v[40:41], v[40:41], 0 op_sel_hi:[1,0]
	v_mov_b32_e32 v42, v33
	v_mov_b32_e32 v43, v69
	v_exp_f32_e32 v74, v54
	v_pk_add_f32 v[40:41], v[42:43], v[40:41]
	v_mov_b32_e32 v42, v34
	v_mov_b32_e32 v43, v70
	v_exp_f32_e32 v75, v55
	s_waitcnt lgkmcnt(2)
	v_mfma_f32_32x32x16_bf16 v[0:15], v[86:89], v[134:137], v[0:15]
	v_add_f32_e64 v40, v42, v40
	v_add_f32_e64 v41, v43, v41
	v_mov_b32_e32 v42, v35
	v_mov_b32_e32 v43, v71
	v_exp_f32_e32 v48, v56
	v_pk_add_f32 v[40:41], v[42:43], v[40:41]
	v_mov_b32_e32 v42, v64
	v_mov_b32_e32 v43, v72
	v_mfma_f32_32x32x16_bf16 v[16:31], v[78:81], v[134:137], v[16:31]
	v_exp_f32_e32 v49, v57
	v_pk_add_f32 v[40:41], v[42:43], v[40:41]
	v_mov_b32_e32 v42, v65
	v_mov_b32_e32 v43, v73
	v_exp_f32_e32 v50, v58
	v_pk_add_f32 v[40:41], v[42:43], v[40:41]
	v_mov_b32_e32 v42, v66
	v_mov_b32_e32 v43, v74
	v_exp_f32_e32 v51, v59
	v_pk_add_f32 v[40:41], v[42:43], v[40:41]
	v_mov_b32_e32 v42, v67
	v_mov_b32_e32 v43, v75
	v_exp_f32_e32 v52, v60
	v_exp_f32_e32 v54, v44
	v_pk_add_f32 v[40:41], v[42:43], v[40:41]
	v_mov_b32_e32 v42, v36
	v_mov_b32_e32 v43, v48
	v_exp_f32_e32 v53, v61
	v_exp_f32_e32 v55, v45
	v_pk_add_f32 v[40:41], v[42:43], v[40:41]
	v_mov_b32_e32 v42, v37
	v_mov_b32_e32 v43, v49
	v_exp_f32_e32 v58, v62
	v_exp_f32_e32 v56, v46
	v_pk_add_f32 v[40:41], v[42:43], v[40:41]
	v_mov_b32_e32 v42, v38
	v_mov_b32_e32 v43, v50
	v_exp_f32_e32 v59, v63
	v_exp_f32_e32 v57, v47
	s_waitcnt lgkmcnt(0)
	v_mfma_f32_32x32x16_bf16 v[0:15], v[90:93], v[138:141], v[0:15]
	v_add_f32_e64 v40, v42, v40
	v_add_f32_e64 v41, v43, v41
	v_mov_b32_e32 v42, v39
	v_mov_b32_e32 v43, v51
	v_add_f32_e64 v40, v42, v40
	v_add_f32_e64 v41, v43, v41
	v_mov_b32_e32 v42, v54
	v_mov_b32_e32 v43, v52
	v_pk_add_f32 v[40:41], v[42:43], v[40:41]
	v_mfma_f32_32x32x16_bf16 v[16:31], v[82:85], v[138:141], v[16:31]
	v_mov_b32_e32 v42, v55
	v_mov_b32_e32 v43, v53
	v_add_f32_e64 v40, v42, v40
	v_add_f32_e64 v41, v43, v41
	v_mov_b32_e32 v42, v56
	v_mov_b32_e32 v43, v58
	v_pk_add_f32 v[40:41], v[42:43], v[40:41]
	v_mov_b32_e32 v42, v57
	v_mov_b32_e32 v43, v59
	v_pk_add_f32 v[40:41], v[42:43], v[40:41]
	s_nop 0
	v_pk_add_f32 v[40:41], v[40:41], v[40:41] op_sel:[0,1] op_sel_hi:[1,0]
	s_nop 0
	v_cmp_lt_f32_e32 vcc, s1, v40
	v_mov_b32_e32 v160, v40
	s_cbranch_vccnz .LBB0_354
	v_cvt_pk_bf16_f32 v40, v68, v69
	v_cvt_pk_bf16_f32 v41, v70, v71
	v_cvt_pk_bf16_f32 v42, v72, v73
	v_cvt_pk_bf16_f32 v43, v74, v75
	v_cvt_pk_bf16_f32 v32, v32, v33
	v_cvt_pk_bf16_f32 v33, v34, v35
	v_cvt_pk_bf16_f32 v34, v64, v65
	v_cvt_pk_bf16_f32 v35, v66, v67
	v_cvt_pk_bf16_f32 v44, v48, v49
	v_cvt_pk_bf16_f32 v45, v50, v51
	v_cvt_pk_bf16_f32 v46, v52, v53
	v_cvt_pk_bf16_f32 v47, v58, v59
	v_cvt_pk_bf16_f32 v36, v36, v37
	v_cvt_pk_bf16_f32 v37, v38, v39
	v_cvt_pk_bf16_f32 v38, v54, v55
	v_cvt_pk_bf16_f32 v39, v56, v57
	s_branch .LBB0_355
